# adds: attention LDS words (work-item broadcast, per-wave distance bounds) via ds_write/ds_read instead of flat ops that drained vmcnt
# baseline (speedup 1.0000x reference)
; DI void attn_phase(const Params& p, int layer, char* smem) {
;     ...
;   for (;;) {
;     __syncthreads();
;     if (threadIdx.x == 0) *s_item = atomicAdd(counter, 1);
;     __syncthreads();
;     const int item = *s_item;
;     if (item >= 64 * (NCH3 + NCH2 + 2)) break;
;     int head, qt, ch;
;     if (item < 64 * NCH3) { head = 3; qt = 63 - item / NCH3; ch = (item % NCH3) | (NCH3 << 8); }
;     else if (item < 64 * (NCH3 + NCH2)) { const int j = item - 64 * NCH3; head = 2; qt = 63 - j / NCH2; ch = (j % NCH2) | (NCH2 << 8); }
;     else if (item < 64 * (NCH3 + NCH2 + 1)) { head = 1; qt = 63 - (item - 64 * (NCH3 + NCH2)); ch = 1 << 8; }
;     else { head = 0; qt = 63 - (item - 64 * (NCH3 + NCH2 + 1)); ch = 1 << 8; }
.LBB0_180:
	s_or_b64 exec, exec, s[2:3]
	s_mov_b64 s[2:3], src_shared_base
	s_waitcnt vmcnt(0) lgkmcnt(1)
	v_readfirstlane_b32 s2, v2
	v_mov_b32_e32 v123, s3
	s_nop 0
	v_add_u32_e32 v0, s2, v0
	ds_write_b32 v122, v0
	s_waitcnt lgkmcnt(0)
.LBB0_181:
	s_or_b64 exec, exec, s[0:1]
	s_waitcnt lgkmcnt(0)
	s_barrier
	ds_read_b32 v0, v126
	s_waitcnt lgkmcnt(0)
	s_mov_b64 s[0:1], -1
	s_waitcnt lgkmcnt(0)
	v_cmp_gt_i32_e32 vcc, s6, v0
	s_and_saveexec_b64 s[70:71], vcc
	s_cbranch_execz .LBB0_176
	v_cmp_gt_i32_e64 s[2:3], s33, v0
	v_cmp_lt_i32_e32 vcc, s82, v0
	s_and_saveexec_b64 s[0:1], vcc
	s_xor_b64 s[0:1], exec, s[0:1]
	s_cbranch_execz .LBB0_192
	v_cmp_lt_u32_e32 vcc, s83, v0
	s_and_saveexec_b64 s[4:5], vcc
	s_xor_b64 s[4:5], exec, s[4:5]
	s_cbranch_execz .LBB0_189
	v_cmp_lt_u32_e32 vcc, s84, v0
	s_and_saveexec_b64 s[72:73], vcc
	s_xor_b64 s[72:73], exec, s[72:73]
	v_sub_u32_e32 v129, 0x17f, v0
	s_or_saveexec_b64 s[72:73], s[72:73]
	v_mov_b32_e32 v2, 0
	s_xor_b64 exec, exec, s[72:73]
	v_sub_u32_e32 v129, 0x13f, v0
	v_mov_b32_e32 v2, 1
	s_or_b64 exec, exec, s[72:73]

; template <int TYPE>
; DI void attn_item(const Params& p, int layer, int head, int qt, int dil, int res, int chunk, char* smem) {
;     ...
;     __syncthreads();
;     if (lane == 0) dred[wid] = D;
;     __syncthreads();
;     const float Dblk = fmaxf(fmaxf(fmaxf(dred[0], dred[1]), fmaxf(dred[2], dred[3])), fmaxf(fmaxf(dred[4], dred[5]), fmaxf(dred[6], dred[7])));
;     const float fs = floorf(((float)Q0 - Dblk - 63.f) * (1.f / 64.f));
;     if (fs > 0.f) kt_lo = (int)fs;
;     const int nch = chunk >> 8, cc = chunk & 255;
;     if (nch > 1) {
;       const int cs = (kt_hi - kt_lo + nch) / nch;
;       const int lo = kt_lo + cc * cs;
;       const int hi = lo + cs - 1;
;       kt_lo = lo;
;       if (hi < kt_hi) kt_hi = hi;
;     }
.LBB0_196:
	s_or_b64 exec, exec, s[0:1]
	v_mov_b32_e32 v131, v125
	v_mov_b32_e32 v133, v125
	v_mov_b32_e32 v135, v125
	v_mov_b32_e32 v137, v125
	v_mov_b32_e32 v139, v125
	v_mov_b32_e32 v141, v125
	v_mov_b32_e32 v143, v125
	s_waitcnt lgkmcnt(0)
	s_barrier
	ds_read_b32 v0, v124
	ds_read_b32 v5, v130
	ds_read_b32 v6, v132
	ds_read_b32 v7, v134
	ds_read_b32 v8, v136
	ds_read_b32 v9, v138
	ds_read_b32 v10, v140
	ds_read_b32 v11, v142
	s_waitcnt vmcnt(0)
	v_lshrrev_b32_e32 v12, 6, v4
	v_cvt_f32_u32_e32 v4, v4
	v_or_b32_e32 v133, 3, v12
	v_and_b32_e32 v131, 0xff, v3
	s_waitcnt lgkmcnt(0)
	v_max_f32_e32 v0, v0, v0
	v_max_f32_e32 v5, v5, v5
	v_max_f32_e32 v6, v6, v6
	v_max_f32_e32 v7, v7, v7
	v_max_f32_e32 v0, v0, v5
	v_max_f32_e32 v5, v6, v7
	v_max_f32_e32 v10, v10, v10
	v_max_f32_e32 v11, v11, v11
	v_max_f32_e32 v6, v10, v11
	v_max3_f32 v6, v8, v9, v6
	v_max3_f32 v0, v0, v5, v6
	v_sub_f32_e32 v0, v4, v0
	v_add_f32_e32 v0, 0xc27c0000, v0
	v_mul_f32_e32 v0, 0x3c800000, v0
	v_floor_f32_e32 v0, v0
	v_max_f32_e32 v0, 0, v0
	v_cvt_i32_f32_e32 v152, v0
	v_ashrrev_i32_e32 v0, 8, v3
	v_cmp_lt_i32_e32 vcc, 1, v0
	s_and_saveexec_b64 s[0:1], vcc
	s_cbranch_execz .LBB0_198
	v_sub_u32_e32 v3, 0, v0
	v_max_i32_e32 v3, v0, v3
	v_cvt_f32_u32_e32 v4, v3
	v_add_u32_e32 v5, v133, v0
	v_sub_u32_e32 v5, v5, v152
	v_sub_u32_e32 v6, 0, v5
	v_rcp_iflag_f32_e32 v4, v4
	v_sub_u32_e32 v7, 0, v3
	v_xor_b32_e32 v0, v5, v0
	v_max_i32_e32 v5, v5, v6
	v_mul_f32_e32 v4, 0x4f7ffffe, v4
	v_cvt_u32_f32_e32 v4, v4
	v_ashrrev_i32_e32 v0, 31, v0
	v_mul_lo_u32 v6, v7, v4
	v_mul_hi_u32 v6, v4, v6
	v_add_u32_e32 v4, v4, v6
	v_mul_hi_u32 v4, v5, v4
	v_mul_lo_u32 v6, v4, v3
	v_sub_u32_e32 v5, v5, v6
	v_add_u32_e32 v7, 1, v4
	v_cmp_ge_u32_e32 vcc, v5, v3
	v_sub_u32_e32 v6, v5, v3
	s_nop 0
	v_cndmask_b32_e32 v4, v4, v7, vcc
	v_cndmask_b32_e32 v5, v5, v6, vcc
	v_add_u32_e32 v6, 1, v4
	v_cmp_ge_u32_e32 vcc, v5, v3
	s_nop 1
	v_cndmask_b32_e32 v3, v4, v6, vcc
	v_xor_b32_e32 v3, v3, v0
	v_sub_u32_e32 v0, v3, v0
	v_mad_u64_u32 v[152:153], s[4:5], v0, v131, v[152:153]
	v_add3_u32 v0, v0, v152, -1
	v_min_i32_e32 v133, v133, v0

; DI int ltid() { int t = threadIdx.x; asm volatile("" : "+v"(t)); return t; }
; template <int TYPE>
; DI void attn_item(const Params& p, int layer, int head, int qt, int dil, int res, int chunk, char* smem) {
;   const int tid = ltid(), lane = tid & 63, wid = tid >> 6, ql = lane & 31, h = lane >> 5;
;   const u16* proj = (const u16*)(p.ws + OFF_BIG);
;   constexpr int QC = TYPE == 0 ? 0 : TYPE == 1 ? 1152 : 1920;
;   constexpr int KC = TYPE == 0 ? 384 : TYPE == 1 ? 1408 : 2304;
;   constexpr int VC = TYPE == 0 ? 768 : TYPE == 1 ? 1664 : 2688;
;   const int qcol = QC + head * 64, kcol = KC + head * 64, vcol = VC + head * 64;
;   const int Q0 = qt * 256;
;   const int wq0 = Q0 + 32 * wid;
;   const int Uq = wq0 + ql;
;   const size_t tq = (size_t)Uq * dil + res;
;   bf16x8 qf[4];
; #pragma unroll
;   for (int ks = 0; ks < 4; ++ks) qf[ks] = *(const bf16x8*)(proj + tq * DIN + qcol + ks * 16 + h * 8);
; DI void attn_phase(const Params& p, int layer, char* smem) {
;     ...
;   for (;;) {
;     __syncthreads();
;     if (threadIdx.x == 0) *s_item = atomicAdd(counter + 1, 1);
;     __syncthreads();
;     const int j = *s_item;
;     if (j >= 384) break;
;     attn_item<2>(p, layer, j % 6, 63 - j / 6, 1, 0, 0, smem);
.LBB0_227:
	s_or_b64 exec, exec, s[2:3]
	s_mov_b64 s[2:3], src_shared_base
	s_waitcnt vmcnt(0)
	v_readfirstlane_b32 s2, v2
	v_mov_b32_e32 v99, s3
	s_nop 0
	v_add_u32_e32 v0, s2, v0
	ds_write_b32 v98, v0
	s_waitcnt lgkmcnt(0)
.LBB0_228:
	s_or_b64 exec, exec, s[0:1]
	s_waitcnt lgkmcnt(0)
	s_barrier
	ds_read_b32 v0, v102
	s_waitcnt lgkmcnt(0)
	s_mov_b64 s[0:1], -1
	s_waitcnt lgkmcnt(0)
	v_cmp_gt_i32_e32 vcc, s28, v0
	s_and_saveexec_b64 s[54:55], vcc
	s_cbranch_execz .LBB0_223
	v_mul_hi_i32 v2, v0, s33
	v_lshrrev_b32_e32 v3, 31, v2
	v_add_u32_e32 v2, v2, v3
	v_mul_lo_u32 v2, v2, 6
	v_sub_u32_e32 v4, v0, v2
	v_mul_hi_i32 v0, v0, s66
	v_lshrrev_b32_e32 v7, 31, v0
	v_mov_b32_e32 v6, v158
	v_add_lshl_u32 v99, v0, v7, 8
	v_ashrrev_i32_e32 v5, 6, v6
	v_lshlrev_b32_e32 v118, 6, v4
	v_add_u32_e32 v7, 0x3f00, v99
	v_lshlrev_b32_e32 v4, 5, v5
	v_and_b32_e32 v2, 31, v6
	v_add_u32_e32 v130, v4, v7
	v_or_b32_e32 v129, v130, v2
	v_mov_b64_e32 v[8:9], s[12:13]
	v_bfe_u32 v3, v6, 5, 1
	v_mad_i64_i32 v[8:9], s[0:1], v129, s67, v[8:9]
	v_ashrrev_i32_e32 v119, 31, v118
	v_lshl_add_u64 v[8:9], v[118:119], 1, v[8:9]
	v_lshlrev_b32_e32 v0, 4, v3
	v_lshl_add_u64 v[8:9], v[8:9], 0, v[0:1]
	global_load_dwordx4 v[50:53], v[8:9], off offset:3840
	global_load_dwordx4 v[54:57], v[8:9], off offset:3872
	global_load_dwordx4 v[58:61], v[8:9], off offset:3904
	global_load_dwordx4 v[62:65], v[8:9], off offset:3936
	v_cmp_gt_i32_e32 vcc, 8, v6
	s_and_saveexec_b64 s[0:1], vcc
	s_cbranch_execz .LBB0_231
	v_lshl_add_u32 v8, v6, 2, v100
	v_mov_b32_e32 v9, s29
	flat_store_dword v[8:9], v1 sc0 sc1
	s_waitcnt vmcnt(0)

; template <int TYPE>
; DI void attn_item(const Params& p, int layer, int head, int qt, int dil, int res, int chunk, char* smem) {
;     ...
;   const int qcol = QC + head * 64, kcol = KC + head * 64, vcol = VC + head * 64;
;   const int Q0 = qt * 256;
;   const int wq0 = Q0 + 32 * wid;
;   const int Uq = wq0 + ql;
;   const size_t tq = (size_t)Uq * dil + res;
;   bf16x8 qf[4];
; #pragma unroll
;   for (int ks = 0; ks < 4; ++ks) qf[ks] = *(const bf16x8*)(proj + tq * DIN + qcol + ks * 16 + h * 8);
;   char* sK = smem;
;   char* sV = smem + 8192;
;   volatile int* sflag = (volatile int*)(smem + FLG + 32);
;   volatile float* dred = (volatile float*)(smem + FLG + 96);
;   float slope = 0.f;
;   if (TYPE == 0) slope = exp2f(-8.f * (float)(head + 1) / 6.f) * (float)dil * LOG2E;
;   if (TYPE == 1) slope = exp2f(-2.f * (float)(head + 1)) * LOG2E;
;   const int wlim = (TYPE == 0) ? 128 : 0x3fffffff;
;   int kt_hi = (Q0 >> 6) + 3;
;   int kt_lo = 0;
;   float cref = 0.f;
;   if (TYPE == 0) {
;     kt_lo = (Q0 >> 6) - 2;
;     if (kt_lo < 0) kt_lo = 0;
;     const float* kma = (const float*)(p.ws + OFF_KMAX) + layer * 32;
;     const float km2 = kma[2 * head] + kma[2 * head + 1];
;     float qn2 = dot8(qf[0], qf[0]) + dot8(qf[1], qf[1]) + dot8(qf[2], qf[2]) + dot8(qf[3], qf[3]);
;     qn2 += __shfl_xor(qn2, 32);
; DI void attn_phase(const Params& p, int layer, char* smem) {
;     ...
;   for (;;) {
;     __syncthreads();
;     if (threadIdx.x == 0) *s_item = atomicAdd(counter + 2, 1);
;     __syncthreads();
;     const int j = *s_item;
;     if (j >= 1152) break;
;     const int head = j % 6, branch = (j / 6) % 3, n = j / 18;
;     const int dil = branch == 0 ? 1 : branch == 1 ? 4 : 16;
;     attn_item<0>(p, layer, head, n / dil, dil, n % dil, branch, smem);
.LBB0_251:
	s_or_b64 exec, exec, s[2:3]
	s_mov_b64 s[2:3], src_shared_base
	s_waitcnt vmcnt(0)
	v_readfirstlane_b32 s2, v1
	v_mov_b32_e32 v75, s3
	s_nop 0
	v_add_u32_e32 v0, s2, v0
	ds_write_b32 v74, v0
	s_waitcnt lgkmcnt(0)
.LBB0_252:
	s_or_b64 exec, exec, s[0:1]
	s_waitcnt lgkmcnt(0)
	s_barrier
	ds_read_b32 v0, v76
	s_waitcnt lgkmcnt(0)
	s_mov_b64 s[0:1], -1
	s_waitcnt lgkmcnt(0)
	v_cmp_gt_i32_e32 vcc, s33, v0
	s_and_saveexec_b64 s[62:63], vcc
	s_cbranch_execz .LBB0_247
	v_mul_hi_i32 v1, v0, s68
	v_lshrrev_b32_e32 v2, 31, v1
	v_add_u32_e32 v1, v1, v2
	v_mul_lo_u32 v2, v1, 6
	v_sub_u32_e32 v78, v0, v2
	v_mul_hi_i32 v2, v1, s69
	v_lshrrev_b32_e32 v3, 31, v2
	v_add_u32_e32 v2, v2, v3
	v_lshl_add_u32 v2, v2, 1, v2
	v_sub_u32_e32 v80, v1, v2
	v_cmp_eq_u32_e32 vcc, 1, v80
	v_cmp_eq_u32_e64 s[0:1], 0, v80
	v_mul_hi_i32 v0, v0, s70
	v_cndmask_b32_e64 v2, 16, 4, vcc
	v_cndmask_b32_e64 v2, v2, 1, s[0:1]
	v_cvt_f32_ubyte0_e32 v37, v2
	v_rcp_iflag_f32_e32 v3, v37
	v_lshrrev_b32_e32 v1, 31, v0
	v_ashrrev_i32_e32 v0, 2, v0
	v_add_u32_e32 v0, v0, v1
	v_mul_f32_e32 v1, 0x4f7ffffe, v3
	v_cvt_u32_f32_e32 v1, v1
	v_sub_u32_e32 v4, 0, v2
	v_sub_u32_e32 v3, 0, v0
	v_max_i32_e32 v3, v0, v3
	v_mul_lo_u32 v4, v4, v1
	v_mul_hi_u32 v4, v1, v4
	v_add_u32_e32 v1, v1, v4
	v_mul_hi_u32 v1, v3, v1
	v_mul_lo_u32 v4, v1, v2
	v_sub_u32_e32 v3, v3, v4
	v_add_u32_e32 v4, 1, v1
	v_cmp_ge_u32_e64 s[2:3], v3, v2
	v_ashrrev_i32_e32 v32, 31, v0
	v_mov_b32_e32 v39, v158
	v_cndmask_b32_e64 v1, v1, v4, s[2:3]
	v_sub_u32_e32 v4, v3, v2
	v_cndmask_b32_e64 v3, v3, v4, s[2:3]
	v_add_u32_e32 v4, 1, v1
	v_cmp_ge_u32_e64 s[2:3], v3, v2
	v_lshlrev_b32_e32 v84, 6, v78
	v_ashrrev_i32_e32 v38, 6, v39
	v_cndmask_b32_e64 v1, v1, v4, s[2:3]
	v_xor_b32_e32 v33, v1, v32
	v_sub_u32_e32 v3, v33, v32
	v_lshlrev_b32_e32 v35, 5, v38
	v_mul_lo_u32 v1, v3, v2
	v_and_b32_e32 v34, 31, v39
	v_lshl_add_u32 v40, v3, 8, v35
	v_sub_u32_e32 v86, v0, v1
	v_or_b32_e32 v0, v40, v34
	v_cndmask_b32_e64 v2, 4, 2, vcc
	v_ashrrev_i32_e32 v1, 31, v0
	v_cndmask_b32_e64 v79, v2, 0, s[0:1]
	v_lshlrev_b64 v[0:1], v79, v[0:1]
	v_ashrrev_i32_e32 v87, 31, v86
	v_lshl_add_u64 v[82:83], v[0:1], 0, v[86:87]
	v_mov_b64_e32 v[0:1], s[12:13]
	v_mad_u64_u32 v[0:1], s[0:1], v82, s71, v[0:1]
	v_bfe_u32 v36, v39, 5, 1
	v_mad_i32_i24 v1, v83, s71, v1
	v_ashrrev_i32_e32 v85, 31, v84
	v_lshl_add_u64 v[0:1], v[84:85], 1, v[0:1]
	v_lshlrev_b32_e32 v72, 4, v36
	v_lshl_add_u64 v[0:1], v[0:1], 0, v[72:73]
	global_load_dwordx4 v[48:51], v[0:1], off
	global_load_dwordx4 v[52:55], v[0:1], off offset:32
	global_load_dwordx4 v[56:59], v[0:1], off offset:64
	global_load_dwordx4 v[60:63], v[0:1], off offset:96
	v_lshlrev_b32_e32 v0, 2, v3
	v_cmp_lt_i32_e32 vcc, v159, v165
	v_max_i32_e32 v1, 2, v0
	v_or_b32_e32 v99, 3, v0
	v_add_u32_e32 v100, -2, v1
	v_and_b32_e32 v75, 63, v39
	v_lshlrev_b32_e32 v72, 2, v36
	s_waitcnt vmcnt(3)
	v_and_b32_e32 v3, 0xffff0000, v48
	s_waitcnt vmcnt(2)
	v_and_b32_e32 v11, 0xffff0000, v52
	v_lshlrev_b32_e32 v2, 16, v48
	v_lshlrev_b32_e32 v10, 16, v52
	v_mul_f32_e32 v3, v3, v3
	v_mul_f32_e32 v11, v11, v11
	v_lshlrev_b32_e32 v4, 16, v49
	v_lshlrev_b32_e32 v12, 16, v53
	v_fmac_f32_e32 v3, v2, v2
	v_fmac_f32_e32 v11, v10, v10
	v_and_b32_e32 v5, 0xffff0000, v49
	v_and_b32_e32 v13, 0xffff0000, v53
	v_fmac_f32_e32 v3, v4, v4
	v_fmac_f32_e32 v11, v12, v12
	v_lshlrev_b32_e32 v6, 16, v50
	v_lshlrev_b32_e32 v14, 16, v54
	s_waitcnt vmcnt(1)
	v_and_b32_e32 v19, 0xffff0000, v56
	v_fmac_f32_e32 v3, v5, v5
	v_fmac_f32_e32 v11, v13, v13
	v_and_b32_e32 v7, 0xffff0000, v50
	v_and_b32_e32 v15, 0xffff0000, v54
	v_lshlrev_b32_e32 v18, 16, v56
	s_waitcnt vmcnt(0)
	v_and_b32_e32 v27, 0xffff0000, v60
	v_mul_f32_e32 v19, v19, v19
	v_fmac_f32_e32 v3, v6, v6
	v_fmac_f32_e32 v11, v14, v14
	v_lshlrev_b32_e32 v8, 16, v51
	v_lshlrev_b32_e32 v16, 16, v55
	v_lshlrev_b32_e32 v20, 16, v57
	v_lshlrev_b32_e32 v26, 16, v60
	v_mul_f32_e32 v27, v27, v27
	v_fmac_f32_e32 v19, v18, v18
	v_fmac_f32_e32 v3, v7, v7
	v_fmac_f32_e32 v11, v15, v15
	v_and_b32_e32 v9, 0xffff0000, v51
	v_and_b32_e32 v17, 0xffff0000, v55
	v_and_b32_e32 v21, 0xffff0000, v57
	v_lshlrev_b32_e32 v28, 16, v61
	v_fmac_f32_e32 v27, v26, v26
	v_fmac_f32_e32 v19, v20, v20
	v_fmac_f32_e32 v3, v8, v8
	v_fmac_f32_e32 v11, v16, v16
	v_lshlrev_b32_e32 v22, 16, v58
	v_and_b32_e32 v29, 0xffff0000, v61
	v_fmac_f32_e32 v27, v28, v28
	v_fmac_f32_e32 v19, v21, v21
	v_fmac_f32_e32 v3, v9, v9
	v_fmac_f32_e32 v11, v17, v17
	v_and_b32_e32 v23, 0xffff0000, v58
	v_fmac_f32_e32 v19, v22, v22
	v_add_f32_e32 v2, v3, v11
	v_fmac_f32_e32 v27, v29, v29
	v_lshlrev_b32_e32 v3, 16, v62
	v_lshlrev_b32_e32 v24, 16, v59
	v_fmac_f32_e32 v19, v23, v23
	v_fmac_f32_e32 v27, v3, v3
	v_and_b32_e32 v3, 0xffff0000, v62
	v_and_b32_e32 v25, 0xffff0000, v59
	v_fmac_f32_e32 v19, v24, v24
	v_fmac_f32_e32 v27, v3, v3
	v_lshlrev_b32_e32 v3, 16, v63
	v_fmac_f32_e32 v19, v25, v25
	v_fmac_f32_e32 v27, v3, v3
	v_and_b32_e32 v3, 0xffff0000, v63
	v_add_f32_e32 v2, v2, v19
	v_fmac_f32_e32 v27, v3, v3
	v_add_f32_e32 v41, v2, v27
	v_cndmask_b32_e32 v2, v164, v159, vcc
	v_lshlrev_b32_e32 v81, 2, v2
	ds_bpermute_b32 v42, v81, v41
	v_cmp_ge_i32_e32 vcc, v99, v100
	s_and_saveexec_b64 s[0:1], vcc
	s_xor_b64 s[64:65], exec, s[0:1]
	s_cbranch_execz .LBB0_261
; template <int TYPE>
; DI void attn_item(const Params& p, int layer, int head, int qt, int dil, int res, int chunk, char* smem) {
;     ...
;   float slope = 0.f;
;   if (TYPE == 0) slope = exp2f(-8.f * (float)(head + 1) / 6.f) * (float)dil * LOG2E;
;   if (TYPE == 1) slope = exp2f(-2.f * (float)(head + 1)) * LOG2E;
;   const int wlim = (TYPE == 0) ? 128 : 0x3fffffff;
;   int kt_hi = (Q0 >> 6) + 3;
;   int kt_lo = 0;
;   float cref = 0.f;
;   if (TYPE == 0) {
;     kt_lo = (Q0 >> 6) - 2;
;     if (kt_lo < 0) kt_lo = 0;
;     const float* kma = (const float*)(p.ws + OFF_KMAX) + layer * 32;
;     const float km2 = kma[2 * head] + kma[2 * head + 1];
;     float qn2 = dot8(qf[0], qf[0]) + dot8(qf[1], qf[1]) + dot8(qf[2], qf[2]) + dot8(qf[3], qf[3]);
;     qn2 += __shfl_xor(qn2, 32);
;     const float R = sqrtf(qn2 * km2) * 1.01f + 0.01f;
;     cref = fmaxf(0.f, R - 60.f);
;     ...
;   const int kkey0 = tid >> 3, kchunk = tid & 7;
;   const int vkey = tid & 63, vdc0 = tid >> 6;
;   const int vk5 = vkey & 31;
;   const int vpos = (vkey & 32) | (vk5 & 0x13) | ((vk5 & 8) >> 1) | ((vk5 & 4) << 1);
;   uint4 kreg0, vreg0;
;     ...
;   ATT_PREFETCH((kt_hi >= kt_lo) ? kt_hi : 0);
	v_lshlrev_b32_e32 v0, 1, v78
	v_ashrrev_i32_e32 v1, 31, v0
	v_lshl_add_u64 v[0:1], v[0:1], 2, s[30:31]
	global_load_dwordx2 v[0:1], v[0:1], off
	v_add_u32_e32 v72, 0x180, v84
	v_ashrrev_i32_e32 v101, 3, v39
	v_lshlrev_b32_e32 v6, 4, v39
	v_lshlrev_b32_e32 v12, 6, v99
	v_mov_b32_e32 v7, v73
	v_lshlrev_b32_e32 v13, 1, v39
	v_and_b32_e32 v14, 48, v39
	v_lshlrev_b64 v[10:11], 1, v[72:73]
	v_and_b32_e32 v72, 0x70, v6
	v_or_b32_e32 v6, v75, v12
	v_add_u32_e32 v12, v101, v12
	s_waitcnt lgkmcnt(0)
	v_add_f32_e32 v20, v41, v42
	v_and_or_b32 v23, v13, 8, v14
	v_and_b32_e32 v41, 6, v13
	v_lshlrev_b64 v[6:7], v79, v[6:7]
	v_ashrrev_i32_e32 v13, 31, v12
	v_mov_b64_e32 v[8:9], s[12:13]
	v_lshl_add_u64 v[14:15], s[12:13], 0, v[10:11]
	v_lshl_add_u64 v[6:7], v[6:7], 0, v[86:87]
	v_lshlrev_b64 v[12:13], v79, v[12:13]
	v_add_u32_e32 v5, 1, v78
	v_add_u32_e32 v2, 0x300, v84
	v_mov_b32_e32 v3, v73
	v_lshlrev_b32_e32 v4, 3, v38
	v_lshl_add_u64 v[88:89], v[14:15], 0, v[72:73]
	v_mad_u64_u32 v[14:15], s[0:1], v6, s71, v[8:9]
	v_lshl_add_u64 v[12:13], v[12:13], 0, v[86:87]
	v_cvt_f32_i32_e32 v22, v5
	v_ashrrev_i32_e32 v5, 31, v4
	v_lshlrev_b64 v[2:3], 1, v[2:3]
	v_mad_i32_i24 v15, v7, s71, v15
	v_mad_u64_u32 v[6:7], s[0:1], v12, s71, v[8:9]
	v_lshl_add_u64 v[16:17], s[12:13], 0, v[2:3]
	v_lshlrev_b64 v[18:19], 1, v[4:5]
	v_lshl_add_u64 v[2:3], v[14:15], 0, v[2:3]
	v_mad_i32_i24 v7, v13, s71, v7
	v_lshl_add_u64 v[2:3], v[2:3], 0, v[18:19]
	v_lshl_add_u64 v[6:7], v[6:7], 0, v[10:11]
	global_load_dwordx4 v[64:67], v[2:3], off
	v_lshl_add_u64 v[2:3], v[6:7], 0, v[72:73]
	global_load_dwordx4 v[68:71], v[2:3], off
	v_lshl_add_u64 v[90:91], v[16:17], 0, v[18:19]
	v_mul_f32_e32 v16, 0xc1000000, v22
	v_div_scale_f32 v8, s[0:1], s72, s72, v16
	v_rcp_f32_e32 v12, v8
	v_div_scale_f32 v9, vcc, v16, s72, v16
	v_lshrrev_b32_e32 v23, 3, v23
	v_fma_f32 v2, -v8, v12, 1.0
	v_fmac_f32_e32 v12, v2, v12
	v_mul_f32_e32 v2, v9, v12
	v_fma_f32 v3, -v8, v2, v9
	v_fmac_f32_e32 v2, v3, v12
	v_fma_f32 v3, -v8, v2, v9
	v_div_fmas_f32 v2, v3, v12, v2
	v_div_fixup_f32 v2, v2, s72, v16
	v_cmp_gt_f32_e32 vcc, s73, v2
	v_and_b32_e32 v21, 8, v39
	v_lshrrev_b32_e32 v24, 1, v101
	v_cndmask_b32_e32 v3, 0, v96, vcc
	v_add_f32_e32 v2, v2, v3
	v_cndmask_b32_e32 v3, 0, v97, vcc
	v_exp_f32_e32 v2, v2
	v_lshlrev_b32_e32 v72, 2, v36
	v_add_u32_e32 v13, v35, v34
	v_xor_b32_e32 v5, v24, v39
	v_ldexp_f32 v2, v2, v3
	v_mul_f32_e32 v2, v2, v37
	v_mul_f32_e32 v92, 0x3fb8aa3b, v2
	v_sub_u32_e32 v13, v13, v72
	v_lshlrev_b32_e32 v5, 4, v5
	v_add_u32_e32 v106, 0xffffff1f, v13
	v_lshlrev_b32_e32 v13, 8, v33
	v_lshlrev_b32_e32 v14, 8, v32
	v_or_b32_e32 v102, 31, v40
	v_add_u32_e32 v103, 0xffffff80, v40
	s_waitcnt vmcnt(2)
	v_add_f32_e32 v0, v0, v1
	v_mul_f32_e32 v0, v0, v20
	v_mul_f32_e32 v1, 0x4f800000, v0
	v_cmp_gt_f32_e32 vcc, s74, v0
	v_lshlrev_b32_e32 v40, 7, v101
	v_and_b32_e32 v5, 0x70, v5
	v_cndmask_b32_e32 v0, v0, v1, vcc
	v_sqrt_f32_e32 v1, v0
	v_sub_u32_e32 v13, v13, v14
	v_mov_b32_e32 v16, v73
	v_mov_b32_e32 v17, v73
	v_add_u32_e32 v2, -1, v1
	v_add_u32_e32 v3, 1, v1
	v_fma_f32 v6, -v2, v1, v0
	v_fma_f32 v7, -v3, v1, v0
	v_cmp_ge_f32_e64 s[0:1], 0, v6
	v_lshlrev_b32_e32 v6, 2, v38
	v_bitop3_b32 v6, v6, v23, 4 bitop3:0x6c
	v_cndmask_b32_e64 v1, v1, v2, s[0:1]
	v_cmp_lt_f32_e64 s[0:1], 0, v7
	v_lshlrev_b32_e32 v6, 4, v6
	v_or_b32_e32 v107, 0xdf, v13
	v_cndmask_b32_e64 v1, v1, v3, s[0:1]
	v_lshlrev_b32_e32 v3, 10, v38
	v_or3_b32 v3, v3, v6, v21
	v_or_b32_e32 v6, 2, v4
	v_lshlrev_b32_e32 v7, 7, v6
	v_lshrrev_b32_e32 v6, 1, v6
	v_bitop3_b32 v6, v6, v23, 5 bitop3:0x6c
	v_lshlrev_b32_e32 v6, 4, v6
	v_or3_b32 v6, v7, v6, v21
	v_or_b32_e32 v7, 3, v4
	v_lshlrev_b32_e32 v8, 7, v7
	v_lshrrev_b32_e32 v7, 1, v7
	v_bitop3_b32 v7, v7, v23, 5 bitop3:0x6c
	v_lshlrev_b32_e32 v7, 4, v7
	v_or3_b32 v7, v8, v7, v21
	v_or_b32_e32 v8, 4, v4
	v_lshlrev_b32_e32 v9, 7, v8
	v_lshrrev_b32_e32 v8, 1, v8
	v_bitop3_b32 v8, v8, v23, 6 bitop3:0x6c
	v_lshlrev_b32_e32 v8, 4, v8
	v_or3_b32 v8, v9, v8, v21
	v_or_b32_e32 v9, 5, v4
	v_lshlrev_b32_e32 v10, 7, v9
	v_lshrrev_b32_e32 v9, 1, v9
	v_bitop3_b32 v9, v9, v23, 6 bitop3:0x6c
	v_lshlrev_b32_e32 v9, 4, v9
	v_or3_b32 v9, v10, v9, v21
	v_or_b32_e32 v10, 6, v4
	v_mul_f32_e32 v2, 0x37800000, v1
	v_lshlrev_b32_e32 v11, 7, v10
	v_lshrrev_b32_e32 v10, 1, v10
	v_cndmask_b32_e32 v1, v1, v2, vcc
	v_cmp_class_f32_e32 vcc, v0, v94
	v_bitop3_b32 v10, v10, v23, 7 bitop3:0x6c
	v_lshlrev_b32_e32 v10, 4, v10
	v_cndmask_b32_e32 v0, v1, v0, vcc
	v_or_b32_e32 v4, 7, v4
	v_fmamk_f32 v0, v0, 0x3f8147ae, v95
	v_or3_b32 v10, v11, v10, v21
	v_lshlrev_b32_e32 v11, 7, v4
	v_lshrrev_b32_e32 v4, 1, v4
	v_add_f32_e32 v0, 0xc2700000, v0
	v_bitop3_b32 v4, v4, v23, 7 bitop3:0x6c
	v_max_f32_e32 v105, 0, v0
	v_lshrrev_b32_e32 v0, 1, v39
	v_bfe_u32 v1, v39, 1, 3
	v_lshlrev_b32_e32 v4, 4, v4
	v_or3_b32 v4, v11, v4, v21
	v_bitop3_b32 v0, v36, v0, 7 bitop3:0x78
	v_bitop3_b32 v11, v36, v1, 2 bitop3:0x36
	v_bitop3_b32 v12, v36, v1, 4 bitop3:0x36
	v_bitop3_b32 v1, v36, v1, 6 bitop3:0x36
	v_lshlrev_b32_e32 v2, 7, v34
	v_lshlrev_b32_e32 v0, 4, v0
	v_lshlrev_b32_e32 v11, 4, v11
	v_lshlrev_b32_e32 v12, 4, v12
	v_lshlrev_b32_e32 v1, 4, v1
	v_mov_b32_e32 v18, v73
	v_mov_b32_e32 v19, v73
	v_mov_b32_e32 v20, v73
	v_mov_b32_e32 v21, v73
	v_mov_b32_e32 v22, v73
	v_mov_b32_e32 v23, v73
	v_mov_b32_e32 v24, v73
	v_mov_b32_e32 v25, v73
	v_mov_b32_e32 v26, v73
	v_mov_b32_e32 v27, v73
	v_mov_b32_e32 v28, v73
	v_mov_b32_e32 v29, v73
	v_mov_b32_e32 v30, v73
	v_mov_b32_e32 v31, v73
	v_add_u32_e32 v108, v5, v40
	v_add_u32_e32 v109, v3, v41
	v_add_u32_e32 v110, v6, v41
	v_add_u32_e32 v111, v7, v41
	v_add_u32_e32 v112, v8, v41
	v_add_u32_e32 v113, v9, v41
	v_add_u32_e32 v114, v10, v41
	v_add_u32_e32 v115, v4, v41
	v_add_u32_e32 v116, v2, v0
	v_add_u32_e32 v117, v2, v11
	v_add_u32_e32 v118, v2, v12
	v_add_u32_e32 v119, v2, v1
	v_mov_b64_e32 v[0:1], v[16:17]
	v_mov_b32_e32 v93, v92
	v_mov_b32_e32 v104, 0
	s_mov_b64 s[66:67], 0
	v_mov_b64_e32 v[2:3], v[18:19]
	v_mov_b64_e32 v[4:5], v[20:21]
	v_mov_b64_e32 v[6:7], v[22:23]
	v_mov_b64_e32 v[8:9], v[24:25]
	v_mov_b64_e32 v[10:11], v[26:27]
	v_mov_b64_e32 v[12:13], v[28:29]
	v_mov_b64_e32 v[14:15], v[30:31]
	s_branch .LBB0_256

; DI void attn_phase(const Params& p, int layer, char* smem) {
;     ...
;   for (;;) {
;     __syncthreads();
;     if (threadIdx.x == 0) *s_item = atomicAdd(counter, 1);
;     __syncthreads();
;     const int item = *s_item;
;     if (item >= 64 * (NCH3 + NCH2 + 2)) break;
;     int head, qt, ch;
;     if (item < 64 * NCH3) { head = 3; qt = 63 - item / NCH3; ch = (item % NCH3) | (NCH3 << 8); }
;     else if (item < 64 * (NCH3 + NCH2)) { const int j = item - 64 * NCH3; head = 2; qt = 63 - j / NCH2; ch = (j % NCH2) | (NCH2 << 8); }
;     else if (item < 64 * (NCH3 + NCH2 + 1)) { head = 1; qt = 63 - (item - 64 * (NCH3 + NCH2)); ch = 1 << 8; }
;     else { head = 0; qt = 63 - (item - 64 * (NCH3 + NCH2 + 1)); ch = 1 << 8; }
.LBB0_557:
	s_or_b64 exec, exec, s[0:1]
	s_waitcnt lgkmcnt(0)
	s_barrier
	ds_read_b32 v0, v126
	s_waitcnt lgkmcnt(0)
	s_mov_b64 s[0:1], -1
	s_waitcnt lgkmcnt(0)
	v_cmp_gt_i32_e32 vcc, s6, v0
	s_and_saveexec_b64 s[62:63], vcc
	s_cbranch_execz .LBB0_552
	v_cmp_gt_i32_e64 s[2:3], s75, v0
	v_cmp_lt_i32_e32 vcc, s76, v0
	s_and_saveexec_b64 s[0:1], vcc
	s_xor_b64 s[0:1], exec, s[0:1]
	s_cbranch_execz .LBB0_568
	v_cmp_lt_u32_e32 vcc, s77, v0
	s_and_saveexec_b64 s[4:5], vcc
	s_xor_b64 s[4:5], exec, s[4:5]
	s_cbranch_execz .LBB0_565
	v_cmp_lt_u32_e32 vcc, s78, v0
	s_and_saveexec_b64 s[64:65], vcc
	s_xor_b64 s[64:65], exec, s[64:65]
	v_sub_u32_e32 v129, 0x17f, v0
	s_or_saveexec_b64 s[64:65], s[64:65]
	v_mov_b32_e32 v2, 0
	s_xor_b64 exec, exec, s[64:65]
	v_sub_u32_e32 v129, 0x13f, v0
	v_mov_b32_e32 v2, 1
	s_or_b64 exec, exec, s[64:65]

; DI int ltid() { int t = threadIdx.x; asm volatile("" : "+v"(t)); return t; }
; template <int TYPE>
; DI void attn_item(const Params& p, int layer, int head, int qt, int dil, int res, int chunk, char* smem) {
;   const int tid = ltid(), lane = tid & 63, wid = tid >> 6, ql = lane & 31, h = lane >> 5;
;   const u16* proj = (const u16*)(p.ws + OFF_BIG);
;   constexpr int QC = TYPE == 0 ? 0 : TYPE == 1 ? 1152 : 1920;
;   constexpr int KC = TYPE == 0 ? 384 : TYPE == 1 ? 1408 : 2304;
;   constexpr int VC = TYPE == 0 ? 768 : TYPE == 1 ? 1664 : 2688;
;   const int qcol = QC + head * 64, kcol = KC + head * 64, vcol = VC + head * 64;
;   const int Q0 = qt * 256;
;   const int wq0 = Q0 + 32 * wid;
;   const int Uq = wq0 + ql;
;   const size_t tq = (size_t)Uq * dil + res;
;   bf16x8 qf[4];
; #pragma unroll
;   for (int ks = 0; ks < 4; ++ks) qf[ks] = *(const bf16x8*)(proj + tq * DIN + qcol + ks * 16 + h * 8);
; DI void attn_phase(const Params& p, int layer, char* smem) {
;     ...
;   for (;;) {
;     __syncthreads();
;     if (threadIdx.x == 0) *s_item = atomicAdd(counter + 1, 1);
;     __syncthreads();
;     const int j = *s_item;
;     if (j >= 384) break;
;     attn_item<2>(p, layer, j % 6, 63 - j / 6, 1, 0, 0, smem);
.LBB0_604:
	s_or_b64 exec, exec, s[0:1]
	s_waitcnt lgkmcnt(0)
	s_barrier
	ds_read_b32 v0, v102
	s_waitcnt lgkmcnt(0)
	s_mov_b64 s[0:1], -1
	s_waitcnt lgkmcnt(0)
	v_cmp_gt_i32_e32 vcc, s18, v0
	s_and_saveexec_b64 s[44:45], vcc
	s_cbranch_execz .LBB0_599
	v_mul_hi_i32 v2, v0, s58
	v_lshrrev_b32_e32 v3, 31, v2
	v_add_u32_e32 v2, v2, v3
	v_mul_lo_u32 v2, v2, 6
	v_sub_u32_e32 v4, v0, v2
	v_mul_hi_i32 v0, v0, s59
	v_lshrrev_b32_e32 v7, 31, v0
	v_mov_b32_e32 v6, v158
	v_add_lshl_u32 v99, v0, v7, 8
	v_ashrrev_i32_e32 v5, 6, v6
	v_lshlrev_b32_e32 v118, 6, v4
	v_add_u32_e32 v7, 0x3f00, v99
	v_lshlrev_b32_e32 v4, 5, v5
	v_and_b32_e32 v2, 31, v6
	v_add_u32_e32 v130, v4, v7
	v_or_b32_e32 v129, v130, v2
	v_mov_b64_e32 v[8:9], s[12:13]
	v_bfe_u32 v3, v6, 5, 1
	v_mad_i64_i32 v[8:9], s[0:1], v129, s60, v[8:9]
	v_ashrrev_i32_e32 v119, 31, v118
	v_lshl_add_u64 v[8:9], v[118:119], 1, v[8:9]
	v_lshlrev_b32_e32 v0, 4, v3
	v_lshl_add_u64 v[8:9], v[8:9], 0, v[0:1]
	global_load_dwordx4 v[50:53], v[8:9], off offset:3840
	global_load_dwordx4 v[54:57], v[8:9], off offset:3872
	global_load_dwordx4 v[58:61], v[8:9], off offset:3904
	global_load_dwordx4 v[62:65], v[8:9], off offset:3936
	v_cmp_gt_i32_e32 vcc, 8, v6
	s_and_saveexec_b64 s[0:1], vcc
	s_cbranch_execz .LBB0_607
	v_lshl_add_u32 v8, v6, 2, v100
	v_mov_b32_e32 v9, s19
	flat_store_dword v[8:9], v1 sc0 sc1
	s_waitcnt vmcnt(0)

; template <int TYPE>
; DI void attn_item(const Params& p, int layer, int head, int qt, int dil, int res, int chunk, char* smem) {
;     ...
;   const int qcol = QC + head * 64, kcol = KC + head * 64, vcol = VC + head * 64;
;   const int Q0 = qt * 256;
;   const int wq0 = Q0 + 32 * wid;
;   const int Uq = wq0 + ql;
;   const size_t tq = (size_t)Uq * dil + res;
;   bf16x8 qf[4];
; #pragma unroll
;   for (int ks = 0; ks < 4; ++ks) qf[ks] = *(const bf16x8*)(proj + tq * DIN + qcol + ks * 16 + h * 8);
;   char* sK = smem;
;   char* sV = smem + 8192;
;   volatile int* sflag = (volatile int*)(smem + FLG + 32);
;   volatile float* dred = (volatile float*)(smem + FLG + 96);
;   float slope = 0.f;
;   if (TYPE == 0) slope = exp2f(-8.f * (float)(head + 1) / 6.f) * (float)dil * LOG2E;
;   if (TYPE == 1) slope = exp2f(-2.f * (float)(head + 1)) * LOG2E;
;   const int wlim = (TYPE == 0) ? 128 : 0x3fffffff;
;   int kt_hi = (Q0 >> 6) + 3;
;   int kt_lo = 0;
;   float cref = 0.f;
;   if (TYPE == 0) {
;     kt_lo = (Q0 >> 6) - 2;
;     if (kt_lo < 0) kt_lo = 0;
;     const float* kma = (const float*)(p.ws + OFF_KMAX) + layer * 32;
;     const float km2 = kma[2 * head] + kma[2 * head + 1];
;     float qn2 = dot8(qf[0], qf[0]) + dot8(qf[1], qf[1]) + dot8(qf[2], qf[2]) + dot8(qf[3], qf[3]);
;     qn2 += __shfl_xor(qn2, 32);
; DI void attn_phase(const Params& p, int layer, char* smem) {
;     ...
;   for (;;) {
;     __syncthreads();
;     if (threadIdx.x == 0) *s_item = atomicAdd(counter + 2, 1);
;     __syncthreads();
;     const int j = *s_item;
;     if (j >= 1152) break;
;     const int head = j % 6, branch = (j / 6) % 3, n = j / 18;
;     const int dil = branch == 0 ? 1 : branch == 1 ? 4 : 16;
;     attn_item<0>(p, layer, head, n / dil, dil, n % dil, branch, smem);
.LBB0_628:
	s_or_b64 exec, exec, s[0:1]
	s_waitcnt lgkmcnt(0)
	s_barrier
	ds_read_b32 v0, v76
	s_waitcnt lgkmcnt(0)
	s_mov_b64 s[0:1], -1
	s_waitcnt lgkmcnt(0)
	v_cmp_gt_i32_e32 vcc, s58, v0
	s_and_saveexec_b64 s[52:53], vcc
	s_cbranch_execz .LBB0_623
	v_mul_hi_i32 v1, v0, s59
	v_lshrrev_b32_e32 v2, 31, v1
	v_add_u32_e32 v1, v1, v2
	v_mul_lo_u32 v2, v1, 6
	v_sub_u32_e32 v78, v0, v2
	v_mul_hi_i32 v2, v1, s60
	v_lshrrev_b32_e32 v3, 31, v2
	v_add_u32_e32 v2, v2, v3
	v_lshl_add_u32 v2, v2, 1, v2
	v_sub_u32_e32 v80, v1, v2
	v_cmp_eq_u32_e32 vcc, 1, v80
	v_cmp_eq_u32_e64 s[0:1], 0, v80
	v_mul_hi_i32 v0, v0, s61
	v_cndmask_b32_e64 v2, 16, 4, vcc
	v_cndmask_b32_e64 v2, v2, 1, s[0:1]
	v_cvt_f32_ubyte0_e32 v37, v2
	v_rcp_iflag_f32_e32 v3, v37
	v_lshrrev_b32_e32 v1, 31, v0
	v_ashrrev_i32_e32 v0, 2, v0
	v_add_u32_e32 v0, v0, v1
	v_mul_f32_e32 v1, 0x4f7ffffe, v3
	v_cvt_u32_f32_e32 v1, v1
	v_sub_u32_e32 v4, 0, v2
	v_sub_u32_e32 v3, 0, v0
	v_max_i32_e32 v3, v0, v3
	v_mul_lo_u32 v4, v4, v1
	v_mul_hi_u32 v4, v1, v4
	v_add_u32_e32 v1, v1, v4
	v_mul_hi_u32 v1, v3, v1
	v_mul_lo_u32 v4, v1, v2
	v_sub_u32_e32 v3, v3, v4
	v_add_u32_e32 v4, 1, v1
	v_cmp_ge_u32_e64 s[2:3], v3, v2
	v_ashrrev_i32_e32 v32, 31, v0
	v_mov_b32_e32 v39, v158
	v_cndmask_b32_e64 v1, v1, v4, s[2:3]
	v_sub_u32_e32 v4, v3, v2
	v_cndmask_b32_e64 v3, v3, v4, s[2:3]
	v_add_u32_e32 v4, 1, v1
	v_cmp_ge_u32_e64 s[2:3], v3, v2
	v_lshlrev_b32_e32 v84, 6, v78
	v_ashrrev_i32_e32 v38, 6, v39
	v_cndmask_b32_e64 v1, v1, v4, s[2:3]
	v_xor_b32_e32 v33, v1, v32
	v_sub_u32_e32 v3, v33, v32
	v_lshlrev_b32_e32 v35, 5, v38
	v_mul_lo_u32 v1, v3, v2
	v_and_b32_e32 v34, 31, v39
	v_lshl_add_u32 v40, v3, 8, v35
	v_sub_u32_e32 v86, v0, v1
	v_or_b32_e32 v0, v40, v34
	v_cndmask_b32_e64 v2, 4, 2, vcc
	v_ashrrev_i32_e32 v1, 31, v0
	v_cndmask_b32_e64 v79, v2, 0, s[0:1]
	v_lshlrev_b64 v[0:1], v79, v[0:1]
	v_ashrrev_i32_e32 v87, 31, v86
	v_lshl_add_u64 v[82:83], v[0:1], 0, v[86:87]
	v_mov_b64_e32 v[0:1], s[12:13]
	v_mad_u64_u32 v[0:1], s[0:1], v82, s62, v[0:1]
	v_bfe_u32 v36, v39, 5, 1
	v_mad_i32_i24 v1, v83, s62, v1
	v_ashrrev_i32_e32 v85, 31, v84
	v_lshl_add_u64 v[0:1], v[84:85], 1, v[0:1]
	v_lshlrev_b32_e32 v72, 4, v36
	v_lshl_add_u64 v[0:1], v[0:1], 0, v[72:73]
	global_load_dwordx4 v[48:51], v[0:1], off
	global_load_dwordx4 v[52:55], v[0:1], off offset:32
	global_load_dwordx4 v[56:59], v[0:1], off offset:64
	global_load_dwordx4 v[60:63], v[0:1], off offset:96
	v_lshlrev_b32_e32 v0, 2, v3
	v_max_i32_e32 v1, 2, v0
	v_or_b32_e32 v81, 3, v0
	v_add_u32_e32 v99, -2, v1
	v_and_b32_e32 v75, 63, v39
	v_cmp_ge_i32_e32 vcc, v81, v99
	v_lshlrev_b32_e32 v72, 2, v36
	s_waitcnt vmcnt(3)
	v_and_b32_e32 v3, 0xffff0000, v48
	s_waitcnt vmcnt(2)
	v_and_b32_e32 v11, 0xffff0000, v52
	v_lshlrev_b32_e32 v2, 16, v48
	v_lshlrev_b32_e32 v10, 16, v52
	v_mul_f32_e32 v3, v3, v3
	v_mul_f32_e32 v11, v11, v11
	v_lshlrev_b32_e32 v4, 16, v49
	v_lshlrev_b32_e32 v12, 16, v53
	v_fmac_f32_e32 v3, v2, v2
	v_fmac_f32_e32 v11, v10, v10
	v_and_b32_e32 v5, 0xffff0000, v49
	v_and_b32_e32 v13, 0xffff0000, v53
	v_fmac_f32_e32 v3, v4, v4
	v_fmac_f32_e32 v11, v12, v12
	v_lshlrev_b32_e32 v6, 16, v50
	v_lshlrev_b32_e32 v14, 16, v54
	s_waitcnt vmcnt(1)
	v_and_b32_e32 v19, 0xffff0000, v56
	v_fmac_f32_e32 v3, v5, v5
	v_fmac_f32_e32 v11, v13, v13
	v_and_b32_e32 v7, 0xffff0000, v50
	v_and_b32_e32 v15, 0xffff0000, v54
	v_lshlrev_b32_e32 v18, 16, v56
	s_waitcnt vmcnt(0)
	v_and_b32_e32 v27, 0xffff0000, v60
	v_mul_f32_e32 v19, v19, v19
	v_fmac_f32_e32 v3, v6, v6
	v_fmac_f32_e32 v11, v14, v14
	v_lshlrev_b32_e32 v8, 16, v51
	v_lshlrev_b32_e32 v16, 16, v55
	v_lshlrev_b32_e32 v20, 16, v57
	v_lshlrev_b32_e32 v26, 16, v60
	v_mul_f32_e32 v27, v27, v27
	v_fmac_f32_e32 v19, v18, v18
	v_fmac_f32_e32 v3, v7, v7
	v_fmac_f32_e32 v11, v15, v15
	v_and_b32_e32 v9, 0xffff0000, v51
	v_and_b32_e32 v17, 0xffff0000, v55
	v_and_b32_e32 v21, 0xffff0000, v57
	v_lshlrev_b32_e32 v28, 16, v61
	v_fmac_f32_e32 v27, v26, v26
	v_fmac_f32_e32 v19, v20, v20
	v_fmac_f32_e32 v3, v8, v8
	v_fmac_f32_e32 v11, v16, v16
	v_lshlrev_b32_e32 v22, 16, v58
	v_and_b32_e32 v29, 0xffff0000, v61
	v_fmac_f32_e32 v27, v28, v28
	v_fmac_f32_e32 v19, v21, v21
	v_fmac_f32_e32 v3, v9, v9
	v_fmac_f32_e32 v11, v17, v17
	v_and_b32_e32 v23, 0xffff0000, v58
	v_fmac_f32_e32 v19, v22, v22
	v_add_f32_e32 v2, v3, v11
	v_fmac_f32_e32 v27, v29, v29
	v_lshlrev_b32_e32 v3, 16, v62
	v_lshlrev_b32_e32 v24, 16, v59
	v_fmac_f32_e32 v19, v23, v23
	v_fmac_f32_e32 v27, v3, v3
	v_and_b32_e32 v3, 0xffff0000, v62
	v_and_b32_e32 v25, 0xffff0000, v59
	v_fmac_f32_e32 v19, v24, v24
	v_fmac_f32_e32 v27, v3, v3
	v_lshlrev_b32_e32 v3, 16, v63
	v_fmac_f32_e32 v19, v25, v25
	v_fmac_f32_e32 v27, v3, v3
	v_and_b32_e32 v3, 0xffff0000, v63
	v_add_f32_e32 v2, v2, v19
	v_fmac_f32_e32 v27, v3, v3
	v_add_f32_e32 v41, v2, v27
	ds_bpermute_b32 v42, v159, v41
	s_and_saveexec_b64 s[0:1], vcc
	s_xor_b64 s[54:55], exec, s[0:1]
	s_cbranch_execz .LBB0_637
; template <int TYPE>
; DI void attn_item(const Params& p, int layer, int head, int qt, int dil, int res, int chunk, char* smem) {
;     ...
;   float slope = 0.f;
;   if (TYPE == 0) slope = exp2f(-8.f * (float)(head + 1) / 6.f) * (float)dil * LOG2E;
;   if (TYPE == 1) slope = exp2f(-2.f * (float)(head + 1)) * LOG2E;
;   const int wlim = (TYPE == 0) ? 128 : 0x3fffffff;
;   int kt_hi = (Q0 >> 6) + 3;
;   int kt_lo = 0;
;   float cref = 0.f;
;   if (TYPE == 0) {
;     kt_lo = (Q0 >> 6) - 2;
;     if (kt_lo < 0) kt_lo = 0;
;     const float* kma = (const float*)(p.ws + OFF_KMAX) + layer * 32;
;     const float km2 = kma[2 * head] + kma[2 * head + 1];
;     float qn2 = dot8(qf[0], qf[0]) + dot8(qf[1], qf[1]) + dot8(qf[2], qf[2]) + dot8(qf[3], qf[3]);
;     qn2 += __shfl_xor(qn2, 32);
;     const float R = sqrtf(qn2 * km2) * 1.01f + 0.01f;
;     cref = fmaxf(0.f, R - 60.f);
;     ...
;   const int kkey0 = tid >> 3, kchunk = tid & 7;
;   const int vkey = tid & 63, vdc0 = tid >> 6;
;   const int vk5 = vkey & 31;
;   const int vpos = (vkey & 32) | (vk5 & 0x13) | ((vk5 & 8) >> 1) | ((vk5 & 4) << 1);
;   uint4 kreg0, vreg0;
;     ...
;   ATT_PREFETCH((kt_hi >= kt_lo) ? kt_hi : 0);
	v_lshlrev_b32_e32 v0, 1, v78
	v_ashrrev_i32_e32 v1, 31, v0
	v_lshl_add_u64 v[0:1], v[0:1], 2, s[34:35]
	global_load_dwordx2 v[0:1], v[0:1], off
	v_add_u32_e32 v72, 0x180, v84
	v_ashrrev_i32_e32 v100, 3, v39
	v_lshlrev_b32_e32 v6, 4, v39
	v_lshlrev_b32_e32 v12, 6, v81
	v_mov_b32_e32 v7, v73
	v_lshlrev_b32_e32 v13, 1, v39
	v_and_b32_e32 v14, 48, v39
	v_lshlrev_b64 v[10:11], 1, v[72:73]
	v_and_b32_e32 v72, 0x70, v6
	v_or_b32_e32 v6, v75, v12
	v_add_u32_e32 v12, v100, v12
	s_waitcnt lgkmcnt(0)
	v_add_f32_e32 v20, v41, v42
	v_and_or_b32 v23, v13, 8, v14
	v_and_b32_e32 v41, 6, v13
	v_lshlrev_b64 v[6:7], v79, v[6:7]
	v_ashrrev_i32_e32 v13, 31, v12
	v_mov_b64_e32 v[8:9], s[12:13]
	v_lshl_add_u64 v[14:15], s[12:13], 0, v[10:11]
	v_lshl_add_u64 v[6:7], v[6:7], 0, v[86:87]
	v_lshlrev_b64 v[12:13], v79, v[12:13]
	v_add_u32_e32 v5, 1, v78
	v_add_u32_e32 v2, 0x300, v84
	v_mov_b32_e32 v3, v73
	v_lshlrev_b32_e32 v4, 3, v38
	v_lshl_add_u64 v[88:89], v[14:15], 0, v[72:73]
	v_mad_u64_u32 v[14:15], s[0:1], v6, s62, v[8:9]
	v_lshl_add_u64 v[12:13], v[12:13], 0, v[86:87]
	v_cvt_f32_i32_e32 v22, v5
	v_ashrrev_i32_e32 v5, 31, v4
	v_lshlrev_b64 v[2:3], 1, v[2:3]
	v_mad_i32_i24 v15, v7, s62, v15
	v_mad_u64_u32 v[6:7], s[0:1], v12, s62, v[8:9]
	v_lshl_add_u64 v[16:17], s[12:13], 0, v[2:3]
	v_lshlrev_b64 v[18:19], 1, v[4:5]
	v_lshl_add_u64 v[2:3], v[14:15], 0, v[2:3]
	v_mad_i32_i24 v7, v13, s62, v7
	v_lshl_add_u64 v[2:3], v[2:3], 0, v[18:19]
	v_lshl_add_u64 v[6:7], v[6:7], 0, v[10:11]
	global_load_dwordx4 v[64:67], v[2:3], off
	v_lshl_add_u64 v[2:3], v[6:7], 0, v[72:73]
	global_load_dwordx4 v[68:71], v[2:3], off
	v_lshl_add_u64 v[90:91], v[16:17], 0, v[18:19]
	v_mul_f32_e32 v16, 0xc1000000, v22
	v_div_scale_f32 v8, s[0:1], s63, s63, v16
	v_rcp_f32_e32 v12, v8
	v_div_scale_f32 v9, vcc, v16, s63, v16
	v_lshrrev_b32_e32 v23, 3, v23
	v_fma_f32 v2, -v8, v12, 1.0
	v_fmac_f32_e32 v12, v2, v12
	v_mul_f32_e32 v2, v9, v12
	v_fma_f32 v3, -v8, v2, v9
	v_fmac_f32_e32 v2, v3, v12
	v_fma_f32 v3, -v8, v2, v9
	v_div_fmas_f32 v2, v3, v12, v2
	v_div_fixup_f32 v2, v2, s63, v16
	v_cmp_gt_f32_e32 vcc, s64, v2
	v_and_b32_e32 v21, 8, v39
	v_lshrrev_b32_e32 v24, 1, v100
	v_cndmask_b32_e32 v3, 0, v96, vcc
	v_add_f32_e32 v2, v2, v3
	v_cndmask_b32_e32 v3, 0, v97, vcc
	v_exp_f32_e32 v2, v2
	v_lshlrev_b32_e32 v72, 2, v36
	v_add_u32_e32 v13, v35, v34
	v_xor_b32_e32 v5, v24, v39
	v_ldexp_f32 v2, v2, v3
	v_mul_f32_e32 v2, v2, v37
	v_mul_f32_e32 v92, 0x3fb8aa3b, v2
	v_sub_u32_e32 v13, v13, v72
	v_lshlrev_b32_e32 v5, 4, v5
	v_add_u32_e32 v105, 0xffffff1f, v13
	v_lshlrev_b32_e32 v13, 8, v33
	v_lshlrev_b32_e32 v14, 8, v32
	v_or_b32_e32 v101, 31, v40
	v_add_u32_e32 v102, 0xffffff80, v40
	s_waitcnt vmcnt(2)
	v_add_f32_e32 v0, v0, v1
	v_mul_f32_e32 v0, v0, v20
	v_mul_f32_e32 v1, 0x4f800000, v0
	v_cmp_gt_f32_e32 vcc, s65, v0
	v_lshlrev_b32_e32 v40, 7, v100
	v_and_b32_e32 v5, 0x70, v5
	v_cndmask_b32_e32 v0, v0, v1, vcc
	v_sqrt_f32_e32 v1, v0
	v_sub_u32_e32 v13, v13, v14
	v_mov_b32_e32 v16, v73
	v_mov_b32_e32 v17, v73
	v_add_u32_e32 v2, -1, v1
	v_add_u32_e32 v3, 1, v1
	v_fma_f32 v6, -v2, v1, v0
	v_fma_f32 v7, -v3, v1, v0
	v_cmp_ge_f32_e64 s[0:1], 0, v6
	v_lshlrev_b32_e32 v6, 2, v38
	v_bitop3_b32 v6, v6, v23, 4 bitop3:0x6c
	v_cndmask_b32_e64 v1, v1, v2, s[0:1]
	v_cmp_lt_f32_e64 s[0:1], 0, v7
	v_lshlrev_b32_e32 v6, 4, v6
	v_or_b32_e32 v106, 0xdf, v13
	v_cndmask_b32_e64 v1, v1, v3, s[0:1]
	v_lshlrev_b32_e32 v3, 10, v38
	v_or3_b32 v3, v3, v6, v21
	v_or_b32_e32 v6, 2, v4
	v_lshlrev_b32_e32 v7, 7, v6
	v_lshrrev_b32_e32 v6, 1, v6
	v_bitop3_b32 v6, v6, v23, 5 bitop3:0x6c
	v_lshlrev_b32_e32 v6, 4, v6
	v_or3_b32 v6, v7, v6, v21
	v_or_b32_e32 v7, 3, v4
	v_lshlrev_b32_e32 v8, 7, v7
	v_lshrrev_b32_e32 v7, 1, v7
	v_bitop3_b32 v7, v7, v23, 5 bitop3:0x6c
	v_lshlrev_b32_e32 v7, 4, v7
	v_or3_b32 v7, v8, v7, v21
	v_or_b32_e32 v8, 4, v4
	v_lshlrev_b32_e32 v9, 7, v8
	v_lshrrev_b32_e32 v8, 1, v8
	v_bitop3_b32 v8, v8, v23, 6 bitop3:0x6c
	v_lshlrev_b32_e32 v8, 4, v8
	v_or3_b32 v8, v9, v8, v21
	v_or_b32_e32 v9, 5, v4
	v_lshlrev_b32_e32 v10, 7, v9
	v_lshrrev_b32_e32 v9, 1, v9
	v_bitop3_b32 v9, v9, v23, 6 bitop3:0x6c
	v_lshlrev_b32_e32 v9, 4, v9
	v_or3_b32 v9, v10, v9, v21
	v_or_b32_e32 v10, 6, v4
	v_mul_f32_e32 v2, 0x37800000, v1
	v_lshlrev_b32_e32 v11, 7, v10
	v_lshrrev_b32_e32 v10, 1, v10
	v_cndmask_b32_e32 v1, v1, v2, vcc
	v_cmp_class_f32_e32 vcc, v0, v94
	v_bitop3_b32 v10, v10, v23, 7 bitop3:0x6c
	v_lshlrev_b32_e32 v10, 4, v10
	v_cndmask_b32_e32 v0, v1, v0, vcc
	v_or_b32_e32 v4, 7, v4
	v_fmamk_f32 v0, v0, 0x3f8147ae, v95
	v_or3_b32 v10, v11, v10, v21
	v_lshlrev_b32_e32 v11, 7, v4
	v_lshrrev_b32_e32 v4, 1, v4
	v_add_f32_e32 v0, 0xc2700000, v0
	v_bitop3_b32 v4, v4, v23, 7 bitop3:0x6c
	v_max_f32_e32 v104, 0, v0
	v_lshrrev_b32_e32 v0, 1, v39
	v_bfe_u32 v1, v39, 1, 3
	v_lshlrev_b32_e32 v4, 4, v4
	v_or3_b32 v4, v11, v4, v21
	v_bitop3_b32 v0, v36, v0, 7 bitop3:0x78
	v_bitop3_b32 v11, v36, v1, 2 bitop3:0x36
	v_bitop3_b32 v12, v36, v1, 4 bitop3:0x36
	v_bitop3_b32 v1, v36, v1, 6 bitop3:0x36
	v_lshlrev_b32_e32 v2, 7, v34
	v_lshlrev_b32_e32 v0, 4, v0
	v_lshlrev_b32_e32 v11, 4, v11
	v_lshlrev_b32_e32 v12, 4, v12
	v_lshlrev_b32_e32 v1, 4, v1
	v_mov_b32_e32 v18, v73
	v_mov_b32_e32 v19, v73
	v_mov_b32_e32 v20, v73
	v_mov_b32_e32 v21, v73
	v_mov_b32_e32 v22, v73
	v_mov_b32_e32 v23, v73
	v_mov_b32_e32 v24, v73
	v_mov_b32_e32 v25, v73
	v_mov_b32_e32 v26, v73
	v_mov_b32_e32 v27, v73
	v_mov_b32_e32 v28, v73
	v_mov_b32_e32 v29, v73
	v_mov_b32_e32 v30, v73
	v_mov_b32_e32 v31, v73
	v_add_u32_e32 v107, v5, v40
	v_add_u32_e32 v108, v3, v41
	v_add_u32_e32 v109, v6, v41
	v_add_u32_e32 v110, v7, v41
	v_add_u32_e32 v111, v8, v41
	v_add_u32_e32 v112, v9, v41
	v_add_u32_e32 v113, v10, v41
	v_add_u32_e32 v114, v4, v41
	v_add_u32_e32 v115, v2, v0
	v_add_u32_e32 v116, v2, v11
	v_add_u32_e32 v117, v2, v12
	v_add_u32_e32 v118, v2, v1
	v_mov_b64_e32 v[0:1], v[16:17]
	v_mov_b32_e32 v93, v92
	v_mov_b32_e32 v103, 0
	s_mov_b64 s[56:57], 0
	v_mov_b64_e32 v[2:3], v[18:19]
	v_mov_b64_e32 v[4:5], v[20:21]
	v_mov_b64_e32 v[6:7], v[22:23]
	v_mov_b64_e32 v[8:9], v[24:25]
	v_mov_b64_e32 v[10:11], v[26:27]
	v_mov_b64_e32 v[12:13], v[28:29]
	v_mov_b64_e32 v[14:15], v[30:31]
	s_branch .LBB0_632
